# grid barrier: all waiters poll the top-level arrival counter reaching (gen+1)*nx instead of a generation word bumped by the last leader
# speedup vs baseline: 1.0026x; 1.0026x over previous
.LBB0_800:
	s_or_b64 exec, exec, s[10:11]
	v_cvt_f32_u32_e32 v4, v2
	s_waitcnt vmcnt(0)
	v_readfirstlane_b32 s8, v3
	v_sub_u32_e32 v3, 0, v2
	v_rcp_iflag_f32_e32 v4, v4
	v_add_u32_e32 v5, s8, v1
	v_mul_f32_e32 v4, 0x4f7ffffe, v4
	v_cvt_u32_f32_e32 v4, v4
	v_mul_lo_u32 v1, v3, v4
	v_mul_hi_u32 v1, v4, v1
	v_add_u32_e32 v1, v4, v1
	v_mul_hi_u32 v1, v5, v1
	v_mul_lo_u32 v3, v1, v2
	v_sub_u32_e32 v3, v5, v3
	v_add_u32_e32 v4, 1, v1
	v_cmp_ge_u32_e32 vcc, v3, v2
	s_nop 1
	v_cndmask_b32_e32 v1, v1, v4, vcc
	v_sub_u32_e32 v4, v3, v2
	v_cndmask_b32_e32 v3, v3, v4, vcc
	v_add_u32_e32 v4, 1, v1
	v_cmp_ge_u32_e32 vcc, v3, v2
	v_add_u32_e32 v3, 1, v5
	s_nop 0
	v_cndmask_b32_e32 v1, v1, v4, vcc
	v_mul_lo_u32 v4, v2, v1
	v_add_u32_e32 v2, v4, v2
	v_cmp_ne_u32_e32 vcc, v3, v2
	s_and_saveexec_b64 s[8:9], vcc
	s_xor_b64 s[8:9], exec, s[8:9]
	s_cbranch_execz .LBB0_814
	s_waitcnt lgkmcnt(0)
	buffer_inv sc1
	v_add_u32_e32 v7, 1, v1
	v_mul_lo_u32 v7, v7, v0
	s_add_u32 s12, s4, 0x3400
	s_addc_u32 s13, s5, 0
	global_load_dword v0, v129, s[12:13] sc1
	s_waitcnt vmcnt(0)
	v_cmp_gt_u32_e32 vcc, v7, v0
	s_and_saveexec_b64 s[10:11], vcc
	s_cbranch_execz .LBB0_813
	s_mov_b32 s24, 1
	s_mov_b64 s[14:15], 0
	s_branch .LBB0_804

.LBB0_806:
	global_load_dword v0, v129, s[12:13] sc1
	s_add_i32 s24, s24, 1
	s_mov_b64 s[20:21], -1
	s_waitcnt vmcnt(0)
	v_cmp_le_u32_e32 vcc, v7, v0
	s_orn2_b64 s[18:19], vcc, exec
	s_branch .LBB0_803

.LBB0_817:
	s_or_b64 exec, exec, s[10:11]
	s_waitcnt vmcnt(0)
	v_readfirstlane_b32 s8, v2
	v_cvt_f32_u32_e32 v2, v0
	v_sub_u32_e32 v3, 0, v0
	v_add_u32_e32 v1, s8, v1
	s_add_u32 s8, s4, 0x3500
	v_rcp_iflag_f32_e32 v2, v2
	s_addc_u32 s9, s5, 0
	s_mov_b64 s[12:13], -1
	v_mul_f32_e32 v2, 0x4f7ffffe, v2
	v_cvt_u32_f32_e32 v2, v2
	v_mul_lo_u32 v3, v3, v2
	v_mul_hi_u32 v3, v2, v3
	v_add_u32_e32 v2, v2, v3
	v_mul_hi_u32 v2, v1, v2
	v_mul_lo_u32 v3, v2, v0
	v_sub_u32_e32 v3, v1, v3
	v_cmp_ge_u32_e32 vcc, v3, v0
	v_add_u32_e32 v4, 1, v2
	v_add_u32_e32 v1, 1, v1
	v_cndmask_b32_e32 v2, v2, v4, vcc
	v_sub_u32_e32 v4, v3, v0
	v_cndmask_b32_e32 v3, v3, v4, vcc
	v_cmp_ge_u32_e32 vcc, v3, v0
	v_add_u32_e32 v3, 1, v2
	s_nop 0
	v_cndmask_b32_e32 v2, v2, v3, vcc
	v_mul_lo_u32 v3, v0, v2
	v_add_u32_e32 v0, v3, v0
	v_cmp_ne_u32_e32 vcc, v1, v0
	v_mov_b32_e32 v7, v0
	v_mov_b64_e32 v[0:1], s[8:9]
	s_and_saveexec_b64 s[10:11], vcc
	s_cbranch_execz .LBB0_831
	v_mov_b32_e32 v5, 0x3400
	global_load_dword v0, v5, s[4:5] sc1
	s_mov_b64 s[16:17], 0
	s_waitcnt vmcnt(0)
	v_cmp_gt_u32_e32 vcc, v7, v0
	s_and_saveexec_b64 s[14:15], vcc
	s_cbranch_execz .LBB0_830
	s_add_u32 s12, s4, 0x200
	s_addc_u32 s13, s5, 0
	s_mov_b32 s24, 1
	s_mov_b64 s[4:5], 0
	s_branch .LBB0_821

.LBB0_823:
	v_mov_b32_e32 v6, 0x3200
	global_load_dword v0, v6, s[12:13] sc1
	s_add_i32 s24, s24, 1
	s_mov_b64 s[20:21], -1
	s_waitcnt vmcnt(0)
	v_cmp_le_u32_e32 vcc, v7, v0
	s_orn2_b64 s[18:19], vcc, exec
	s_branch .LBB0_820
